# flat release: non-leader workgroups poll the top-level barrier generation word directly, per-XCD generation hop removed
# baseline (speedup 1.0000x reference)
.LBB0_170:
	s_or_b64 exec, exec, s[10:11]
	v_cvt_f32_u32_e32 v5, v3
	s_waitcnt vmcnt(0)
	v_readfirstlane_b32 s8, v4
	v_sub_u32_e32 v4, 0, v3
	v_rcp_iflag_f32_e32 v5, v5
	v_add_u32_e32 v6, s8, v2
	v_mul_f32_e32 v5, 0x4f7ffffe, v5
	v_cvt_u32_f32_e32 v5, v5
	v_mul_lo_u32 v2, v4, v5
	v_mul_hi_u32 v2, v5, v2
	v_add_u32_e32 v2, v5, v2
	v_mul_hi_u32 v2, v6, v2
	v_mul_lo_u32 v4, v2, v3
	v_sub_u32_e32 v4, v6, v4
	v_add_u32_e32 v5, 1, v2
	v_cmp_ge_u32_e32 vcc, v4, v3
	s_nop 1
	v_cndmask_b32_e32 v2, v2, v5, vcc
	v_sub_u32_e32 v5, v4, v3
	v_cndmask_b32_e32 v4, v4, v5, vcc
	v_add_u32_e32 v5, 1, v2
	v_cmp_ge_u32_e32 vcc, v4, v3
	v_add_u32_e32 v4, 1, v6
	s_nop 0
	v_cndmask_b32_e32 v2, v2, v5, vcc
	v_mul_lo_u32 v5, v3, v2
	v_add_u32_e32 v3, v5, v3
	v_cmp_ne_u32_e32 vcc, v4, v3
	s_and_saveexec_b64 s[8:9], vcc
	s_xor_b64 s[8:9], exec, s[8:9]
	s_cbranch_execz .LBB0_184
	s_waitcnt lgkmcnt(0)
	v_mov_b32_e32 v1, 0x7500
	buffer_inv sc1
	global_load_dword v1, v1, s[46:47] sc1
	s_add_u32 s14, s46, 0x7500
	s_addc_u32 s15, s47, 0
	s_waitcnt vmcnt(0)
	v_cmp_eq_u32_e32 vcc, v1, v2
	s_and_saveexec_b64 s[10:11], vcc
	s_cbranch_execz .LBB0_183
	s_add_u32 s12, s46, 0x4200
	s_addc_u32 s13, s47, 0
	s_mov_b32 s30, 1
	s_mov_b64 s[16:17], 0
	v_mov_b32_e32 v1, 0
	s_branch .LBB0_174

.LBB0_201:
	s_or_b64 exec, exec, s[8:9]
	s_mov_b64 s[8:9], exec
	v_mbcnt_lo_u32_b32 v1, s8, 0
	v_mbcnt_hi_u32_b32 v1, s9, v1
	v_cmp_eq_u32_e32 vcc, 0, v1
	s_waitcnt vmcnt(0)
	s_nop 0
	s_and_saveexec_b64 s[10:11], vcc
	s_cbranch_execz .LBB0_203
	s_bcnt1_i32_b64 s8, s[8:9]
	v_mov_b32_e32 v1, 0x2000
	v_mov_b32_e32 v2, s8
	s_nop 0

.LBB0_265:
	s_or_b64 exec, exec, s[8:9]
	v_cvt_f32_u32_e32 v5, v3
	s_waitcnt vmcnt(0)
	v_readfirstlane_b32 s6, v4
	v_sub_u32_e32 v4, 0, v3
	v_rcp_iflag_f32_e32 v5, v5
	v_add_u32_e32 v6, s6, v2
	v_mul_f32_e32 v5, 0x4f7ffffe, v5
	v_cvt_u32_f32_e32 v5, v5
	v_mul_lo_u32 v2, v4, v5
	v_mul_hi_u32 v2, v5, v2
	v_add_u32_e32 v2, v5, v2
	v_mul_hi_u32 v2, v6, v2
	v_mul_lo_u32 v4, v2, v3
	v_sub_u32_e32 v4, v6, v4
	v_add_u32_e32 v5, 1, v2
	v_cmp_ge_u32_e32 vcc, v4, v3
	s_nop 1
	v_cndmask_b32_e32 v2, v2, v5, vcc
	v_sub_u32_e32 v5, v4, v3
	v_cndmask_b32_e32 v4, v4, v5, vcc
	v_add_u32_e32 v5, 1, v2
	v_cmp_ge_u32_e32 vcc, v4, v3
	v_add_u32_e32 v4, 1, v6
	s_nop 0
	v_cndmask_b32_e32 v2, v2, v5, vcc
	v_mul_lo_u32 v5, v3, v2
	v_add_u32_e32 v3, v5, v3
	v_cmp_ne_u32_e32 vcc, v4, v3
	s_and_saveexec_b64 s[6:7], vcc
	s_xor_b64 s[6:7], exec, s[6:7]
	s_cbranch_execz .LBB0_279
	s_waitcnt lgkmcnt(0)
	v_mov_b32_e32 v1, 0x7500
	buffer_inv sc1
	global_load_dword v1, v1, s[46:47] sc1
	s_add_u32 s12, s46, 0x7500
	s_addc_u32 s13, s47, 0
	s_waitcnt vmcnt(0)
	v_cmp_eq_u32_e32 vcc, v1, v2
	s_and_saveexec_b64 s[8:9], vcc
	s_cbranch_execz .LBB0_278
	s_add_u32 s10, s46, 0x4200
	s_addc_u32 s11, s47, 0
	s_mov_b32 s26, 1
	s_mov_b64 s[14:15], 0
	v_mov_b32_e32 v1, 0
	s_branch .LBB0_269

.LBB0_296:
	s_or_b64 exec, exec, s[6:7]
	s_mov_b64 s[6:7], exec
	v_mbcnt_lo_u32_b32 v1, s6, 0
	v_mbcnt_hi_u32_b32 v1, s7, v1
	v_cmp_eq_u32_e32 vcc, 0, v1
	s_waitcnt vmcnt(0)
	s_nop 0
	s_and_saveexec_b64 s[8:9], vcc
	s_cbranch_execz .LBB0_298
	s_bcnt1_i32_b64 s6, s[6:7]
	v_mov_b32_e32 v1, 0x2000
	v_mov_b32_e32 v2, s6
	s_nop 0

.LBB0_300:
	s_add_u32 s58, s46, 0x800000
	s_addc_u32 s59, s47, 0
	s_add_u32 s0, s46, 0x180000
	v_writelane_b32 v252, s0, 40
	s_addc_u32 s0, s47, 0
	s_cmpk_lt_i32 s2, 0x300
	v_writelane_b32 v252, s0, 41
	s_cselect_b64 s[0:1], -1, 0
	v_writelane_b32 v252, s0, 42
	s_ashr_i32 s60, s2, 31
	v_mbcnt_lo_u32_b32 v2, -1, 0
	v_writelane_b32 v252, s1, 43
	s_lshr_b32 s0, s60, 29
	s_add_i32 s1, s2, s0
	s_ashr_i32 s0, s1, 3
	s_and_b32 s1, s1, -8
	s_sub_i32 s1, s2, s1
	s_add_u32 s4, s46, 0x4200
	s_addc_u32 s5, s47, 0
	s_add_u32 s62, s46, 0x4400
	s_addc_u32 s63, s47, 0
	s_add_u32 s64, s46, 0x4500
	s_addc_u32 s65, s47, 0
	s_add_u32 s8, s46, 0x4600
	s_addc_u32 s9, s47, 0
	s_add_u32 s6, s46, 0x4700
	v_writelane_b32 v252, s4, 44
	s_addc_u32 s7, s47, 0
	s_mul_i32 s10, s1, 0x41
	v_writelane_b32 v252, s5, 45
	s_add_u32 s4, s46, 0x4800
	s_addc_u32 s5, s47, 0
	v_writelane_b32 v252, s4, 46
	s_mov_b32 s49, 0
	v_mov_b32_e32 v99, 0
	v_writelane_b32 v252, s5, 47
	s_add_u32 s4, s46, 0x4900
	s_addc_u32 s5, s47, 0
	v_writelane_b32 v252, s4, 48
	v_mbcnt_hi_u32_b32 v229, -1, v2
	v_mov_b32_e32 v230, 0x4000
	v_writelane_b32 v252, s5, 49
	s_add_u32 s4, s46, 0x4a00
	s_addc_u32 s5, s47, 0
	v_writelane_b32 v252, s4, 50
	v_mov_b32_e32 v248, 0x1b00
	v_mov_b32_e32 v228, 0x2400
	v_writelane_b32 v252, s5, 51
	s_add_u32 s4, s46, 0x4b00
	s_addc_u32 s5, s47, 0
	v_writelane_b32 v252, s4, 52
	v_mov_b32_e32 v196, 0x2d00
	v_mov_b32_e32 v234, 0x1b800
	v_writelane_b32 v252, s5, 53
	s_add_u32 s4, s46, 0x4c00
	s_addc_u32 s5, s47, 0
	v_writelane_b32 v252, s4, 54
	v_mov_b32_e32 v235, 0x13000
	v_not_b32_e32 v236, 63
	v_writelane_b32 v252, s5, 55
	s_add_u32 s4, s46, 0x4d00
	s_addc_u32 s5, s47, 0
	v_writelane_b32 v252, s4, 56
	v_mov_b32_e32 v237, 0xffffff80
	v_mov_b64_e32 v[198:199], 0x1ff
	v_writelane_b32 v252, s5, 57
	s_add_u32 s4, s46, 0x4e00
	s_addc_u32 s5, s47, 0
	v_writelane_b32 v252, s4, 58
	v_mov_b64_e32 v[250:251], 0x800
	v_mov_b64_e32 v[232:233], 0x7ff
	v_writelane_b32 v252, s5, 59
	s_add_u32 s4, s46, 0x4f00
	s_addc_u32 s5, s47, 0
	v_writelane_b32 v252, s4, 60
	s_movk_i32 s51, 0x80
	s_movk_i32 s97, 0xff
	v_writelane_b32 v252, s5, 61
	s_add_u32 s4, s46, 0x5000
	s_addc_u32 s5, s47, 0
	v_writelane_b32 v252, s4, 62
	s_movk_i32 s50, 0x90
	s_movk_i32 s86, 0xc00
	v_writelane_b32 v252, s5, 63
	s_add_u32 s4, s46, 0x5100
	s_addc_u32 s5, s47, 0
	v_writelane_b32 v253, s4, 0
	s_mov_b32 s87, 0x5040100
	s_mov_b32 s55, 0x7060302
	v_writelane_b32 v253, s5, 1
	s_add_u32 s4, s46, 0x5200
	s_addc_u32 s5, s47, 0
	v_writelane_b32 v253, s4, 2
	s_mov_b32 s72, 0xe000000
	s_mov_b32 s73, 0xffff7000
	v_writelane_b32 v253, s5, 3
	s_add_u32 s4, s46, 0x5300
	s_addc_u32 s5, s47, 0
	v_writelane_b32 v253, s4, 4
	s_cmp_eq_u32 s75, 15
	s_mov_b64 s[42:43], 0x80
	v_writelane_b32 v253, s5, 5
	s_cselect_b64 s[4:5], -1, 0
	v_writelane_b32 v253, s4, 6
	s_cmp_eq_u32 s75, 14
	s_mov_b32 s54, 0x3d372713
	v_writelane_b32 v253, s5, 7
	s_cselect_b64 s[4:5], -1, 0
	v_writelane_b32 v253, s4, 8
	s_cmp_eq_u32 s75, 13
	s_mov_b64 s[78:79], 0x10000
	v_writelane_b32 v253, s5, 9
	s_cselect_b64 s[4:5], -1, 0
	v_writelane_b32 v253, s4, 10
	s_cmp_eq_u32 s75, 12
	s_nop 0
	v_writelane_b32 v253, s5, 11
	s_cselect_b64 s[4:5], -1, 0
	v_writelane_b32 v253, s4, 12
	s_cmp_eq_u32 s75, 11
	s_nop 0
	v_writelane_b32 v253, s5, 13
	s_cselect_b64 s[4:5], -1, 0
	v_writelane_b32 v253, s4, 14
	s_cmp_eq_u32 s75, 10
	s_nop 0
	v_writelane_b32 v253, s5, 15
	s_cselect_b64 s[4:5], -1, 0
	v_writelane_b32 v253, s4, 16
	s_cmp_eq_u32 s75, 9
	s_nop 0
	v_writelane_b32 v253, s5, 17
	s_cselect_b64 s[4:5], -1, 0
	v_writelane_b32 v253, s4, 18
	s_cmp_eq_u32 s75, 8
	s_nop 0
	v_writelane_b32 v253, s5, 19
	s_cselect_b64 s[4:5], -1, 0
	v_writelane_b32 v253, s4, 20
	s_cmp_eq_u32 s75, 7
	s_nop 0
	v_writelane_b32 v253, s5, 21
	s_cselect_b64 s[4:5], -1, 0
	v_writelane_b32 v253, s4, 22
	s_cmp_eq_u32 s75, 6
	s_nop 0
	v_writelane_b32 v253, s5, 23
	s_cselect_b64 s[4:5], -1, 0
	v_writelane_b32 v253, s4, 24
	s_cmp_eq_u32 s75, 5
	s_nop 0
	v_writelane_b32 v253, s5, 25
	s_cselect_b64 s[4:5], -1, 0
	v_writelane_b32 v253, s4, 26
	s_cmp_eq_u32 s75, 4
	s_nop 0
	v_writelane_b32 v253, s5, 27
	s_cselect_b64 s[4:5], -1, 0
	v_writelane_b32 v253, s4, 28
	s_cmp_eq_u32 s75, 3
	s_nop 0
	v_writelane_b32 v253, s5, 29
	s_cselect_b64 s[4:5], -1, 0
	v_writelane_b32 v253, s4, 30
	s_cmp_eq_u32 s75, 2
	s_nop 0
	v_writelane_b32 v253, s5, 31
	s_cselect_b64 s[4:5], -1, 0
	v_writelane_b32 v253, s4, 32
	s_cmp_eq_u32 s75, 1
	s_nop 0
	v_writelane_b32 v253, s5, 33
	s_cselect_b64 s[4:5], -1, 0
	v_writelane_b32 v253, s4, 34
	s_cmp_eq_u32 s75, 0
	s_nop 0
	v_writelane_b32 v253, s5, 35
	s_cselect_b64 s[4:5], -1, 0
	v_writelane_b32 v253, s4, 36
	s_nop 1
	v_writelane_b32 v253, s5, 37
	s_lshl_b32 s4, s75, 8
	s_add_u32 s4, s76, s4
	s_addc_u32 s5, s77, 0
	s_mov_b64 s[74:75], s[6:7]
	s_add_u32 s6, s4, 0x1400
	s_addc_u32 s7, s5, 0
	v_writelane_b32 v253, s6, 38
	s_add_u32 s4, s46, 0x7500
	s_addc_u32 s5, s47, 0
	v_writelane_b32 v253, s7, 39
	v_writelane_b32 v253, s4, 40
	s_movk_i32 s76, 0x8000
	s_nop 0
	v_writelane_b32 v253, s5, 41
	s_add_u32 s4, s46, 0x7400
	s_addc_u32 s5, s47, 0
	v_writelane_b32 v253, s4, 42
	s_nop 1
	v_writelane_b32 v253, s5, 43
	s_add_u32 s4, s46, 0x7500
	s_addc_u32 s5, s47, 0
	v_writelane_b32 v253, s4, 44
	s_cmpk_lt_i32 s2, 0x200
	s_nop 0
	v_writelane_b32 v253, s5, 45
	s_cselect_b64 s[4:5], -1, 0
	v_writelane_b32 v253, s4, 46
	s_nop 1
	v_writelane_b32 v253, s5, 47
	s_lshl_b32 s4, s1, 6
	s_cmpk_lt_i32 s2, 0x800
	s_cselect_b64 s[6:7], -1, 0
	v_writelane_b32 v253, s6, 48
	s_lshl_b32 s5, s1, 8
	s_add_u32 s3, s46, 0x198000
	v_writelane_b32 v253, s7, 49
	v_writelane_b32 v253, s3, 50
	s_addc_u32 s3, s47, 0
	s_cmp_gt_i32 s67, 8
	v_writelane_b32 v253, s3, 51
	s_cselect_b64 s[6:7], -1, 0
	s_add_u32 s22, s46, 0x4000000
	v_writelane_b32 v253, s6, 52
	s_addc_u32 s23, s47, 0
	s_add_u32 s3, s46, 0x18800000
	v_writelane_b32 v253, s7, 53
	v_writelane_b32 v253, s3, 54
	s_addc_u32 s3, s47, 0
	v_writelane_b32 v253, s3, 55
	s_add_u32 s3, s46, 0x1000000
	v_writelane_b32 v253, s3, 56
	s_addc_u32 s3, s47, 0
	s_add_u32 s24, s46, 0x8000000
	s_addc_u32 s25, s47, 0
	v_writelane_b32 v253, s3, 57
	s_add_u32 s3, s46, 0x200000
	v_writelane_b32 v253, s3, 58
	s_addc_u32 s3, s47, 0
	v_writelane_b32 v253, s3, 59
	s_cmp_lt_i32 s1, 0
	s_movk_i32 s3, 0x61
	s_cselect_b32 s4, s10, s4
	s_cselect_b32 s10, s3, 0x60
	s_mul_i32 s10, s1, s10
	s_mulk_i32 s1, 0x101
	s_cselect_b32 s1, s1, s5
	s_add_i32 s10, s10, s0
	s_mul_hi_i32 s5, s10, 0x2aaaaaab
	s_lshr_b32 s11, s5, 31
	s_ashr_i32 s5, s5, 3
	s_add_i32 s5, s5, s11
	s_lshl_b32 s14, s5, 3
	s_sub_i32 s11, 0x80, s14
	s_min_i32 s15, s11, 8
	s_ashr_i32 s61, s33, 31
	v_readlane_b32 s6, v252, 2
	s_cmpk_gt_i32 s6, 0xff
	s_cselect_b64 s[12:13], -1, 0
	v_writelane_b32 v253, s12, 60
	s_ashr_i32 s3, s6, 5
	s_add_u32 s7, s46, 0x400000
	v_writelane_b32 v253, s13, 61
	v_writelane_b32 v253, s7, 62
	s_addc_u32 s7, s47, 0
	v_writelane_b32 v254, s3, 0
	s_lshl_b32 s3, s3, 6
	s_add_u32 s12, s46, 0x280000
	v_writelane_b32 v254, s3, 1
	s_addc_u32 s13, s47, 0
	v_writelane_b32 v254, s12, 2
	s_cmpk_lt_i32 s6, 0x100
	v_writelane_b32 v253, s7, 63
	v_writelane_b32 v254, s13, 3
	s_cselect_b64 s[12:13], -1, 0
	v_writelane_b32 v254, s12, 4
	s_mul_i32 s5, s5, 48
	s_nop 0
	v_writelane_b32 v254, s13, 5
	s_add_u32 s12, s46, 0x18000000
	s_addc_u32 s13, s47, 0
	s_add_u32 s34, s46, 0x6000000
	s_addc_u32 s35, s47, 0
	s_add_u32 s84, s46, 0x12000000
	v_writelane_b32 v254, s12, 6
	s_addc_u32 s85, s47, 0
	s_nop 0
	v_writelane_b32 v254, s13, 7
	s_add_u32 s12, s46, 0xa00000
	s_addc_u32 s13, s47, 0
	v_writelane_b32 v254, s12, 8
	s_add_u32 s3, s46, 0x18400000
	s_nop 0
	v_writelane_b32 v254, s13, 9
	v_writelane_b32 v254, s3, 10
	s_addc_u32 s3, s47, 0
	s_add_u32 s12, s46, 0x320000
	v_writelane_b32 v254, s3, 11
	s_addc_u32 s13, s47, 0
	v_writelane_b32 v254, s12, 12
	s_lshl_b32 s3, s6, 3
	s_lshl_b32 s77, s33, 3
	v_writelane_b32 v254, s13, 13
	v_writelane_b32 v254, s3, 14
	s_add_u32 s3, s46, 0x300000
	v_writelane_b32 v254, s3, 15
	s_addc_u32 s3, s47, 0
	v_writelane_b32 v254, s3, 16
	s_add_u32 s3, s46, 0x14000000
	v_writelane_b32 v254, s3, 17
	s_addc_u32 s3, s47, 0
	s_add_u32 s70, s46, 0x328000
	s_addc_u32 s71, s47, 0
	s_cmpk_lg_i32 s33, 0x100
	v_writelane_b32 v254, s3, 18
	s_cselect_b64 s[12:13], -1, 0
	v_writelane_b32 v254, s12, 19
	s_add_u32 s7, s46, 0x340000
	s_nop 0
	v_writelane_b32 v254, s13, 20
	v_writelane_b32 v254, s7, 21
	s_addc_u32 s7, s47, 0
	v_writelane_b32 v254, s7, 22
	s_add_u32 s7, s46, 0xe000000
	v_writelane_b32 v254, s7, 23
	s_addc_u32 s7, s47, 0
	v_writelane_b32 v254, s7, 24
	s_add_u32 s7, s46, 0x17800000
	v_writelane_b32 v254, s7, 25
	s_addc_u32 s7, s47, 0
	v_writelane_b32 v254, s7, 26
	s_add_u32 s7, s46, 0x1600000
	s_addc_u32 s29, s47, 0
	s_add_i32 s4, s4, s0
	s_ashr_i32 s11, s4, 31
	s_lshr_b32 s11, s11, 27
	s_add_i32 s11, s4, s11
	s_and_b32 s12, s11, 0xffffffe0
	s_ashr_i32 s11, s11, 5
	s_sub_i32 s4, s4, s12
	s_sub_i32 s12, 0, s11
	s_lshl_b32 s12, s12, 3
	s_lshl_b32 s17, s11, 3
	s_min_i32 s12, s12, 0xffffff88
	s_sub_i32 s11, 0x80, s17
	s_add_i32 s16, s12, 0x80
	s_min_i32 s18, s11, 8
	s_add_u32 s30, s46, 0x1c00000
	s_addc_u32 s31, s47, 0
	s_add_i32 s0, s1, s0
	s_ashr_i32 s1, s0, 31
	s_lshr_b32 s1, s1, 25
	s_add_i32 s1, s0, s1
	s_ashr_i32 s11, s1, 7
	s_sub_i32 s12, 0, s11
	s_lshl_b32 s12, s12, 3
	s_min_i32 s12, s12, 0xffffff88
	s_add_i32 s19, s12, 0x80
	s_add_u32 s12, s46, 0x220000
	v_writelane_b32 v254, s12, 27
	s_addc_u32 s12, s47, 0
	s_and_b32 s1, s1, 0xffffff80
	s_lshl_b32 s11, s11, 3
	v_writelane_b32 v254, s12, 28
	s_sub_i32 s12, s0, s1
	s_sub_i32 s0, 0x80, s11
	s_min_i32 s13, s0, 8
	s_add_u32 s0, s46, 0x2c00000
	v_writelane_b32 v254, s0, 29
	s_addc_u32 s0, s47, 0
	s_mul_hi_i32 s1, s10, 0xd5555555
	v_writelane_b32 v254, s0, 30
	s_sub_i32 s0, s10, s5
	s_lshr_b32 s5, s1, 31
	s_lshr_b32 s1, s1, 3
	s_add_i32 s1, s1, s5
	s_abs_i32 s5, s15
	v_cvt_f32_u32_e32 v1, s5
	s_sub_i32 s10, 0, s5
	s_lshl_b32 s1, s1, 3
	v_rcp_iflag_f32_e32 v1, v1
	s_nop 0
	v_mul_f32_e32 v1, 0x4f7ffffe, v1
	v_cvt_u32_f32_e32 v1, v1
	s_nop 0
	v_readfirstlane_b32 s20, v1
	s_mul_i32 s10, s10, s20
	s_mul_hi_u32 s10, s20, s10
	s_add_i32 s20, s20, s10
	s_min_i32 s10, s1, 0xffffff88
	s_xor_b32 s1, s0, s15
	s_ashr_i32 s21, s1, 31
	s_abs_i32 s1, s0
	s_mul_hi_u32 s20, s1, s20
	s_mul_i32 s26, s20, s5
	s_sub_i32 s26, s1, s26
	s_addk_i32 s10, 0x80
	s_add_i32 s27, s20, 1
	s_sub_i32 s28, s26, s5
	s_cmp_ge_u32 s26, s5
	s_cselect_b32 s20, s27, s20
	s_cselect_b32 s26, s28, s26
	s_add_i32 s27, s20, 1
	s_cmp_ge_u32 s26, s5
	s_cselect_b32 s5, s27, s20
	s_xor_b32 s5, s5, s21
	s_sub_i32 s26, s5, s21
	s_mul_i32 s5, s26, s15
	s_sub_i32 s5, s0, s5
	s_add_i32 s36, s14, s5
	s_ashr_i32 s37, s36, 31
	s_lshl_b64 s[14:15], s[36:37], 19
	s_add_u32 s38, s22, s14
	s_mov_b32 s20, s26
	s_addc_u32 s39, s23, s15
	s_ashr_i32 s27, s26, 31
	s_lshl_b32 s5, s36, 8
	v_writelane_b32 v254, s20, 31
	s_addk_i32 s5, 0xc000
	s_lshr_b32 s5, s5, 12
	v_writelane_b32 v254, s21, 32
	s_lshl_b64 s[20:21], s[26:27], 19
	v_writelane_b32 v254, s20, 33
	s_add_i32 s5, s5, 2
	s_ashr_i32 s14, s36, 5
	v_writelane_b32 v254, s21, 34
	s_mov_b32 s20, s36
	v_writelane_b32 v254, s20, 35
	s_cmp_lt_i32 s36, 64
	s_cselect_b32 s5, s14, s5
	v_writelane_b32 v254, s21, 36
	v_writelane_b32 v254, s5, 37
	s_add_u32 s14, s38, 0x40000
	v_writelane_b32 v254, s38, 38
	s_addc_u32 s15, s39, 0
	s_abs_i32 s5, s16
	v_cvt_f32_u32_e32 v1, s5
	v_writelane_b32 v254, s39, 39
	v_writelane_b32 v254, s14, 40
	s_mov_b32 s28, 0xc0135761
	v_rcp_iflag_f32_e32 v1, v1
	v_writelane_b32 v254, s15, 41
	s_sub_i32 s14, 0, s5
	v_writelane_b32 v254, s7, 42
	v_mul_f32_e32 v1, 0x4f7ffffe, v1
	v_cvt_u32_f32_e32 v1, v1
	s_nop 0
	v_readfirstlane_b32 s15, v1
	s_mul_i32 s14, s14, s15
	s_mul_hi_u32 s14, s15, s14
	s_add_i32 s15, s15, s14
	s_xor_b32 s14, s4, s16
	s_abs_i32 s16, s4
	s_mul_hi_u32 s15, s16, s15
	s_mul_i32 s20, s15, s5
	s_sub_i32 s20, s16, s20
	s_ashr_i32 s14, s14, 31
	s_add_i32 s21, s15, 1
	s_sub_i32 s26, s20, s5
	s_cmp_ge_u32 s20, s5
	s_cselect_b32 s15, s21, s15
	s_cselect_b32 s20, s26, s20
	s_add_i32 s21, s15, 1
	s_cmp_ge_u32 s20, s5
	s_cselect_b32 s5, s21, s15
	s_xor_b32 s5, s5, s14
	s_sub_i32 s14, s5, s14
	s_ashr_i32 s15, s14, 31
	s_lshl_b64 s[14:15], s[14:15], 19
	s_add_u32 s5, s7, s14
	v_writelane_b32 v254, s5, 43
	v_writelane_b32 v254, s29, 44
	s_addc_u32 s5, s29, s15
	v_writelane_b32 v254, s5, 45
	s_abs_i32 s5, s18
	v_cvt_f32_u32_e32 v1, s5
	s_sub_i32 s14, 0, s5
	s_movk_i32 s29, 0x600
	s_mov_b32 s26, s49
	v_rcp_iflag_f32_e32 v1, v1
	s_nop 0
	v_mul_f32_e32 v1, 0x4f7ffffe, v1
	v_cvt_u32_f32_e32 v1, v1
	s_nop 0
	v_readfirstlane_b32 s15, v1
	s_mul_i32 s14, s14, s15
	s_mul_hi_u32 s14, s15, s14
	s_add_i32 s15, s15, s14
	s_mul_hi_u32 s14, s16, s15
	s_mul_i32 s15, s14, s5
	s_sub_i32 s15, s16, s15
	s_xor_b32 s16, s4, s18
	s_ashr_i32 s16, s16, 31
	s_add_i32 s20, s14, 1
	s_sub_i32 s21, s15, s5
	s_cmp_ge_u32 s15, s5
	s_cselect_b32 s14, s20, s14
	s_cselect_b32 s15, s21, s15
	s_add_i32 s20, s14, 1
	s_cmp_ge_u32 s15, s5
	s_cselect_b32 s5, s20, s14
	s_xor_b32 s5, s5, s16
	s_sub_i32 s16, s5, s16
	s_mul_i32 s5, s16, s18
	s_sub_i32 s4, s4, s5
	s_abs_i32 s5, s19
	v_cvt_f32_u32_e32 v1, s5
	s_mov_b32 s14, s16
	v_writelane_b32 v254, s14, 46
	s_abs_i32 s16, s12
	v_rcp_iflag_f32_e32 v1, v1
	v_writelane_b32 v254, s15, 47
	s_sub_i32 s14, 0, s5
	s_add_i32 s4, s17, s4
	v_mul_f32_e32 v1, 0x4f7ffffe, v1
	v_cvt_u32_f32_e32 v1, v1
	v_writelane_b32 v254, s4, 48
	v_readfirstlane_b32 s15, v1
	s_mul_i32 s14, s14, s15
	s_mul_hi_u32 s14, s15, s14
	s_add_i32 s15, s15, s14
	s_mul_hi_u32 s14, s16, s15
	s_mul_i32 s15, s14, s5
	v_writelane_b32 v254, s5, 49
	s_xor_b32 s4, s12, s19
	s_sub_i32 s15, s16, s15
	s_ashr_i32 s4, s4, 31
	s_add_i32 s17, s14, 1
	s_sub_i32 s18, s15, s5
	s_cmp_ge_u32 s15, s5
	s_cselect_b32 s14, s17, s14
	s_cselect_b32 s15, s18, s15
	s_add_i32 s17, s14, 1
	s_cmp_ge_u32 s15, s5
	s_cselect_b32 s5, s17, s14
	s_xor_b32 s5, s5, s4
	s_sub_i32 s14, s5, s4
	s_ashr_i32 s15, s14, 31
	s_lshl_b64 s[14:15], s[14:15], 19
	v_writelane_b32 v254, s30, 50
	s_add_u32 s4, s30, s14
	v_writelane_b32 v254, s4, 51
	v_writelane_b32 v254, s31, 52
	s_addc_u32 s4, s31, s15
	v_writelane_b32 v254, s4, 53
	s_abs_i32 s4, s13
	v_cvt_f32_u32_e32 v1, s4
	s_sub_i32 s5, 0, s4
	s_xor_b32 s15, s12, s13
	s_ashr_i32 s15, s15, 31
	v_rcp_iflag_f32_e32 v1, v1
	s_nop 0
	v_mul_f32_e32 v1, 0x4f7ffffe, v1
	v_cvt_u32_f32_e32 v1, v1
	s_nop 0
	v_readfirstlane_b32 s14, v1
	s_mul_i32 s5, s5, s14
	s_mul_hi_u32 s5, s14, s5
	s_add_i32 s14, s14, s5
	s_mul_hi_u32 s5, s16, s14
	s_mul_i32 s14, s5, s4
	s_sub_i32 s14, s16, s14
	s_add_i32 s16, s5, 1
	s_sub_i32 s17, s14, s4
	s_cmp_ge_u32 s14, s4
	s_cselect_b32 s5, s16, s5
	s_cselect_b32 s14, s17, s14
	s_add_i32 s16, s5, 1
	s_cmp_ge_u32 s14, s4
	s_cselect_b32 s4, s16, s5
	s_xor_b32 s4, s4, s15
	s_sub_i32 s14, s4, s15
	s_mul_i32 s4, s14, s13
	s_sub_i32 s4, s12, s4
	s_add_i32 s12, s11, s4
	s_ashr_i32 s13, s12, 31
	s_mov_b32 s4, s12
	v_writelane_b32 v254, s4, 54
	s_lshl_b64 s[12:13], s[12:13], 19
	s_add_u32 s12, s22, s12
	v_writelane_b32 v254, s5, 55
	s_mov_b32 s4, s14
	s_addc_u32 s13, s23, s13
	s_ashr_i32 s15, s14, 31
	v_writelane_b32 v254, s4, 56
	s_nop 1
	v_writelane_b32 v254, s5, 57
	s_lshl_b64 s[4:5], s[14:15], 19
	v_writelane_b32 v254, s4, 58
	s_nop 1
	v_writelane_b32 v254, s5, 59
	s_add_u32 s4, s12, 0x40000
	v_writelane_b32 v254, s12, 60
	s_addc_u32 s5, s13, 0
	s_nop 0
	v_writelane_b32 v254, s13, 61
	v_writelane_b32 v254, s4, 62
	s_nop 1
	v_writelane_b32 v254, s5, 63
	s_abs_i32 s4, s33
	v_cvt_f32_u32_e32 v1, s4
	s_sub_i32 s5, 0, s4
	v_rcp_iflag_f32_e32 v1, v1
	s_nop 0
	v_mul_f32_e32 v1, 0x4f7ffffe, v1
	v_cvt_u32_f32_e32 v1, v1
	s_nop 0
	v_readfirstlane_b32 s11, v1
	s_mul_i32 s5, s5, s11
	s_mul_hi_u32 s5, s11, s5
	s_add_i32 s11, s11, s5
	s_lshr_b32 s5, s11, 23
	s_mul_i32 s11, s5, s4
	s_sub_i32 s11, 0x200, s11
	s_sub_i32 s12, s11, s4
	s_add_i32 s13, s5, 1
	s_cmp_ge_u32 s11, s4
	s_cselect_b32 s11, s12, s11
	s_cselect_b32 s5, s13, s5
	s_sub_i32 s12, s11, s4
	s_add_i32 s13, s5, 1
	s_cmp_ge_u32 s11, s4
	s_cselect_b32 s4, s12, s11
	s_cselect_b32 s5, s13, s5
	s_cmp_eq_u32 s4, 0
	s_cselect_b64 s[12:13], -1, 0
	s_xor_b32 s4, s5, s61
	s_sub_i32 s4, s4, s61
	v_writelane_b32 v255, s12, 0
	s_cmp_gt_i32 s4, 0
	s_nop 0
	v_writelane_b32 v255, s13, 1
	s_cselect_b64 s[12:13], -1, 0
	v_writelane_b32 v255, s12, 2
	s_add_i32 s5, s4, -1
	s_nop 0
	v_writelane_b32 v255, s13, 3
	v_writelane_b32 v255, s5, 4
	v_writelane_b32 v255, s4, 5
	s_mul_i32 s4, s4, s33
	s_cmpk_eq_i32 s4, 0x200
	s_cselect_b64 s[4:5], -1, 0
	v_writelane_b32 v255, s4, 6
	s_xor_b32 s0, s0, s10
	s_ashr_i32 s0, s0, 31
	v_writelane_b32 v255, s5, 7
	s_abs_i32 s4, s10
	v_cvt_f32_u32_e32 v1, s4
	s_sub_i32 s5, 0, s4
	v_rcp_iflag_f32_e32 v1, v1
	s_nop 0
	v_mul_f32_e32 v1, 0x4f7ffffe, v1
	v_cvt_u32_f32_e32 v1, v1
	s_nop 0
	v_readfirstlane_b32 s10, v1
	s_mul_i32 s5, s5, s10
	s_mul_hi_u32 s5, s10, s5
	s_add_i32 s10, s10, s5
	s_mul_hi_u32 s5, s1, s10
	s_mul_i32 s10, s5, s4
	s_sub_i32 s1, s1, s10
	s_add_i32 s10, s5, 1
	s_sub_i32 s11, s1, s4
	s_cmp_ge_u32 s1, s4
	s_cselect_b32 s5, s10, s5
	s_cselect_b32 s1, s11, s1
	s_add_i32 s10, s5, 1
	s_cmp_ge_u32 s1, s4
	s_cselect_b32 s1, s10, s5
	s_xor_b32 s1, s1, s0
	s_sub_i32 s0, s1, s0
	s_ashr_i32 s1, s0, 31
	s_lshl_b64 s[0:1], s[0:1], 19
	s_add_u32 s0, s46, s0
	s_addc_u32 s1, s47, s1
	s_add_u32 s4, s0, 0x1300000
	s_addc_u32 s5, s1, 0
	v_writelane_b32 v255, s4, 8
	v_mov_b32_e32 v1, 0x358637bd
	s_mov_b64 s[10:11], -1
	v_writelane_b32 v255, s5, 9
	s_add_u32 s4, s0, 0x1340000
	s_addc_u32 s5, s1, 0
	v_writelane_b32 v255, s4, 10
	s_add_u32 s0, s0, 0x1340080
	s_addc_u32 s1, s1, 0
	v_writelane_b32 v255, s5, 11
	v_writelane_b32 v255, s0, 12
	s_lshl_b32 s96, s33, 10
	s_mov_b32 s3, s96
	v_writelane_b32 v255, s1, 13
	s_lshl_b32 s0, s6, 10
	v_writelane_b32 v255, s0, 14
	s_lshl_b32 s0, s6, 9
	v_writelane_b32 v255, s0, 15
	s_lshl_b32 s0, s33, 9
	v_writelane_b32 v255, s0, 16
	s_add_u32 s0, s46, 0x14011c00
	s_addc_u32 s1, s47, 0
	v_writelane_b32 v255, s0, 17
	s_nop 1
	v_writelane_b32 v255, s1, 18
	s_add_i32 s0, 0, 0xb400
	v_writelane_b32 v255, s0, 19
	s_add_i32 s0, 0, 0x27f20
	v_writelane_b32 v255, s0, 20
	s_add_i32 s0, 0, 0x27f24
	v_writelane_b32 v255, s0, 21
	s_add_i32 s0, 0, 0x13000
	v_writelane_b32 v255, s0, 22
	s_add_i32 s0, 0, 0xdf00
	v_writelane_b32 v255, s0, 23
	v_writelane_b32 v255, s58, 24
	s_mov_b64 s[0:1], 0
	s_nop 0
	v_writelane_b32 v255, s59, 25
	v_writelane_b32 v255, s60, 26
	v_writelane_b32 v255, s62, 27
	s_nop 1
	v_writelane_b32 v255, s63, 28
	v_writelane_b32 v255, s64, 29
	s_nop 1
	v_writelane_b32 v255, s65, 30
	v_writelane_b32 v255, s8, 31
	s_nop 1
	v_writelane_b32 v255, s9, 32
	v_writelane_b32 v255, s74, 33
	s_nop 1
	v_writelane_b32 v255, s75, 34
	v_writelane_b32 v255, s61, 35
	v_writelane_b32 v255, s77, 36
	v_writelane_b32 v255, s70, 37
	s_nop 1
	v_writelane_b32 v255, s71, 38
	s_branch .LBB0_302

.LBB0_415:
	s_or_b64 exec, exec, s[14:15]
	s_mov_b64 s[14:15], exec
	v_mbcnt_lo_u32_b32 v2, s14, 0
	v_mbcnt_hi_u32_b32 v2, s15, v2
	v_cmp_eq_u32_e32 vcc, 0, v2
	s_waitcnt vmcnt(0)
	s_nop 0
	s_and_saveexec_b64 s[20:21], vcc
	s_cbranch_execz .LBB0_417
	s_bcnt1_i32_b64 s4, s[14:15]
	v_mov_b32_e32 v2, s4
	v_readlane_b32 s4, v253, 40
	v_readlane_b32 s5, v253, 41
	s_nop 4
	s_nop 0

.LBB0_554:
	s_or_b64 exec, exec, s[10:11]
	s_mov_b64 s[10:11], exec
	v_mbcnt_lo_u32_b32 v2, s10, 0
	v_mbcnt_hi_u32_b32 v2, s11, v2
	v_cmp_eq_u32_e32 vcc, 0, v2
	s_waitcnt vmcnt(0)
	s_nop 0
	s_and_saveexec_b64 s[12:13], vcc
	s_cbranch_execz .LBB0_556
	s_bcnt1_i32_b64 s4, s[10:11]
	v_mov_b32_e32 v2, s4
	v_readlane_b32 s4, v253, 40
	v_readlane_b32 s5, v253, 41
	s_nop 4
	s_nop 0

.LBB0_985:
	s_or_b64 exec, exec, s[12:13]
	s_mov_b64 s[12:13], exec
	v_mbcnt_lo_u32_b32 v2, s12, 0
	v_mbcnt_hi_u32_b32 v2, s13, v2
	v_cmp_eq_u32_e32 vcc, 0, v2
	s_waitcnt vmcnt(0)
	s_nop 0
	s_and_saveexec_b64 s[14:15], vcc
	s_cbranch_execz .LBB0_987
	s_bcnt1_i32_b64 s4, s[12:13]
	v_mov_b32_e32 v2, s4
	v_readlane_b32 s4, v253, 40
	v_readlane_b32 s5, v253, 41
	s_nop 4
	s_nop 0

.LBB0_1078:
	s_or_b64 exec, exec, s[10:11]
	s_mov_b64 s[10:11], exec
	v_mbcnt_lo_u32_b32 v2, s10, 0
	v_mbcnt_hi_u32_b32 v2, s11, v2
	v_cmp_eq_u32_e32 vcc, 0, v2
	s_waitcnt vmcnt(0)
	s_nop 0
	s_and_saveexec_b64 s[14:15], vcc
	s_cbranch_execz .LBB0_1080
	s_bcnt1_i32_b64 s4, s[10:11]
	v_mov_b32_e32 v2, s4
	v_readlane_b32 s4, v253, 40
	v_readlane_b32 s5, v253, 41
	s_nop 4
	s_nop 0
